# three dead VALU removed at the head of mixer A's tile loop (on top of the one-compare visibility masks)
# baseline (speedup 1.0000x reference)
; template <bool MASKED>
; DI bool attnA_tile_math(const f32x16& Su, const LAS float* bt, int qpos, int kpos0, int kvalid, bool meta_tile, int h, int lane, float& m, float& l, float& corr, bf16x8 (&bfrag)[2]) {
;     ...
;         const int row = (r & 3) + 8 * (r >> 2) + 4 * h;
;         const int dist = qpos - (kpos0 + row);
;         if (MASKED) {
;             const bool vis = (row < kvalid) && (dist >= 0) && (meta_tile || dist < 128);
;             const int di = dist < 0 ? 0 : (dist > 128 ? 128 : dist);
;             const float v = Su[r] * (0.125f * 1.4426950408889634f) + bt[di];
;             sc[r] = vis ? v : -1e30f;
.LBB0_197:
	s_lshl_b32 s4, s31, 5
	s_or_b32 s6, s4, 16
	s_cmp_lt_i32 s31, 0
	s_cselect_b64 s[8:9], -1, 0
	s_and_b64 s[4:5], s[8:9], exec
	s_cselect_b32 s30, 16, 32
	s_cselect_b32 s42, 0, s6
	s_or_b32 s4, s31, s28
	s_cmp_lt_i32 s4, 0
	s_cselect_b64 s[4:5], -1, 0
	s_cmp_le_i32 s31, s86
	v_add_u32_e32 v211, s42, v125
	s_cselect_b64 s[6:7], -1, 0
	s_cmp_ge_i32 s31, s28
	v_sub_u32_e32 v186, v128, v211
	s_cselect_b64 s[10:11], -1, 0
	s_or_b64 s[4:5], s[6:7], s[4:5]
	s_or_b64 s[6:7], s[4:5], s[10:11]
	s_cbranch_scc0 .LfastA
	s_and_b64 s[4:5], s[8:9], exec
	s_cselect_b32 s4, 0x80000000, s15
	s_cselect_b32 s5, 0, s15
	ds_read_b128 v[66:69], v129 offset:6144
	ds_read_b128 v[120:123], v129 offset:7168
	ds_read_b128 v[168:171], v129 offset:8192
	ds_read_b128 v[178:181], v129 offset:9216
	v_cmp_gt_u32_e64 s[36:37], s4, v186
	v_med3_i32 v0, v186, 0, v176
	v_add_u32_e32 v173, -1, v186
	v_cmp_gt_u32_e64 s[38:39], s4, v173
	v_med3_i32 v173, v173, 0, v176
	v_add_u32_e32 v182, -2, v186
	v_cmp_gt_u32_e64 s[40:41], s4, v182
	v_med3_i32 v182, v182, 0, v176
	v_add_u32_e32 v183, -3, v186
	v_cmp_gt_u32_e64 s[44:45], s4, v183
	v_med3_i32 v183, v183, 0, v176
	v_sub_u32_e32 v184, v147, v211
	v_cmp_gt_u32_e64 s[48:49], s4, v184
	v_med3_i32 v184, v184, 0, v176
	v_sub_u32_e32 v185, v148, v211
	v_cmp_gt_u32_e64 s[52:53], s4, v185
	v_med3_i32 v185, v185, 0, v176
	v_sub_u32_e32 v187, v149, v211
	v_cmp_gt_u32_e64 s[56:57], s4, v187
	v_med3_i32 v187, v187, 0, v176
	v_sub_u32_e32 v188, v150, v211
	v_cmp_gt_u32_e64 s[60:61], s4, v188
	v_med3_i32 v188, v188, 0, v176
	v_sub_u32_e32 v189, v151, v211
	v_cmp_gt_u32_e64 s[42:43], s5, v189
	v_med3_i32 v189, v189, 0, v176
	v_sub_u32_e32 v190, v152, v211
	v_cmp_gt_u32_e64 s[46:47], s5, v190
	v_med3_i32 v190, v190, 0, v176
	v_sub_u32_e32 v191, v153, v211
	v_cmp_gt_u32_e64 s[50:51], s5, v191
	v_med3_i32 v191, v191, 0, v176
	v_sub_u32_e32 v192, v158, v211
	v_cmp_gt_u32_e64 s[54:55], s5, v192
	v_med3_i32 v192, v192, 0, v176
	v_sub_u32_e32 v205, v159, v211
	v_cmp_gt_u32_e64 s[58:59], s5, v205
	v_med3_i32 v205, v205, 0, v176
	v_sub_u32_e32 v215, v160, v211
	v_cmp_gt_u32_e64 s[62:63], s5, v215
	v_med3_i32 v215, v215, 0, v176
	v_sub_u32_e32 v216, v161, v211
	v_cmp_gt_u32_e64 s[64:65], s5, v216
	v_med3_i32 v216, v216, 0, v176
	v_sub_u32_e32 v217, v162, v211
	v_cmp_gt_u32_e64 s[66:67], s5, v217
	v_med3_i32 v217, v217, 0, v176
	s_waitcnt lgkmcnt(0)
